# P8->P9: workgroups with 5 P8 tiles leave seam 8 once their XCD finished P8 round 3 and run P9 tiles of the already complete row panels (P9 tile assignment swapped between rank halves)
# speedup vs baseline: 1.0100x; 1.0072x over previous
.LBB0_125:
	s_cmp_gt_i32 s69, 2
	s_cselect_b64 s[0:1], -1, 0
	s_and_b64 s[2:3], s[4:5], s[0:1]
	s_andn2_b64 vcc, exec, s[2:3]
	s_cbranch_vccnz .LBB0_179
	s_waitcnt vmcnt(0)
	s_waitcnt lgkmcnt(0)
	s_barrier
	v_mov_b32_e32 v0, 0x20040
	ds_read_b32 v2, v0
	ds_read_b32 v3, v0 offset:16
	ds_read_b32 v5, v0 offset:8
	s_lshl_b32 s2, s33, 7
	s_add_u32 s2, s2, 0x3600
	v_lshl_add_u32 v0, v199, 2, s2
	v_mov_b32_e32 v6, 2
	v_mov_b32_e32 v7, 2
	s_waitcnt lgkmcnt(0)
	v_cmp_eq_u32_e32 vcc, 0, v3
	s_cbranch_vccnz .Lxl_orig_1
	v_cmp_lt_u32_e32 vcc, 32, v2
	s_cbranch_vccnz .Lxl_orig_1
	v_lshl_add_u32 v1, v5, 2, s2
	v_cmp_lt_u32_e32 vcc, v199, v2
	s_and_saveexec_b64 s[4:5], vcc
	s_cbranch_execz .LBB0_178
	v_cmp_eq_u32_e32 vcc, 0, v199
	s_and_saveexec_b64 s[2:3], vcc
	global_store_dword v1, v6, s[92:93]
	s_mov_b64 exec, s[2:3]
	buffer_inv sc1
	s_mov_b32 s2, 0x20000
.Lxl_poll_1:
	global_load_dword v4, v0, s[92:93] sc1
	s_waitcnt vmcnt(0)
	v_cmp_gt_u32_e32 vcc, v7, v4
	s_cbranch_vccz .LBB0_178
	s_sleep 1
	s_sub_u32 s2, s2, 1
	s_cmp_lg_u32 s2, 0
	s_cbranch_scc1 .Lxl_poll_1
	s_branch .LBB0_178

.LBB0_262:
	s_cmp_gt_i32 s69, 3
	s_cselect_b64 s[0:1], -1, 0
	s_and_b64 s[2:3], s[4:5], s[0:1]
	s_andn2_b64 vcc, exec, s[2:3]
	s_cbranch_vccnz .LBB0_316
	s_waitcnt vmcnt(0)
	s_waitcnt vmcnt(0) lgkmcnt(0)
	s_barrier
	v_mov_b32_e32 v0, 0x20040
	ds_read_b32 v2, v0
	ds_read_b32 v3, v0 offset:16
	ds_read_b32 v5, v0 offset:8
	s_lshl_b32 s2, s33, 7
	s_add_u32 s2, s2, 0x3600
	v_lshl_add_u32 v0, v199, 2, s2
	v_mov_b32_e32 v6, 4
	v_mov_b32_e32 v7, 4
	s_waitcnt lgkmcnt(0)
	v_cmp_eq_u32_e32 vcc, 0, v3
	s_cbranch_vccnz .Lxl_orig_2
	v_cmp_lt_u32_e32 vcc, 32, v2
	s_cbranch_vccnz .Lxl_orig_2
	v_lshl_add_u32 v1, v5, 2, s2
	v_cmp_lt_u32_e32 vcc, v199, v2
	s_and_saveexec_b64 s[4:5], vcc
	s_cbranch_execz .LBB0_315
	v_cmp_eq_u32_e32 vcc, 0, v199
	s_and_saveexec_b64 s[2:3], vcc
	global_store_dword v1, v6, s[92:93]
	s_mov_b64 exec, s[2:3]
	buffer_inv sc1
	s_mov_b32 s2, 0x20000

.LBB0_363:
	s_cmp_gt_i32 s69, 4
	s_cselect_b64 s[0:1], -1, 0
	s_and_b64 s[2:3], s[8:9], s[0:1]
	s_andn2_b64 vcc, exec, s[2:3]
	s_cbranch_vccnz .LBB0_417
	s_waitcnt vmcnt(0)
	s_waitcnt vmcnt(0) lgkmcnt(0)
	s_barrier
	v_mov_b32_e32 v0, 0x20040
	ds_read_b32 v2, v0
	ds_read_b32 v3, v0 offset:16
	ds_read_b32 v5, v0 offset:8
	s_lshl_b32 s2, s33, 7
	s_add_u32 s2, s2, 0x3600
	v_lshl_add_u32 v0, v199, 2, s2
	v_mov_b32_e32 v6, 6
	v_mov_b32_e32 v7, 6
	s_waitcnt lgkmcnt(0)
	v_cmp_eq_u32_e32 vcc, 0, v3
	s_cbranch_vccnz .Lxl_orig_3
	v_cmp_lt_u32_e32 vcc, 32, v2
	s_cbranch_vccnz .Lxl_orig_3
	v_lshl_add_u32 v1, v5, 2, s2
	v_cmp_lt_u32_e32 vcc, v199, v2
	s_and_saveexec_b64 s[4:5], vcc
	s_cbranch_execz .LBB0_416
	v_cmp_eq_u32_e32 vcc, 0, v199
	s_and_saveexec_b64 s[2:3], vcc
	global_store_dword v1, v6, s[92:93]
	s_mov_b64 exec, s[2:3]
	buffer_inv sc1
	s_mov_b32 s2, 0x20000

.LBB0_1502:
	s_cmp_gt_i32 s69, 7
	s_cselect_b64 s[2:3], -1, 0
	s_and_b64 s[0:1], s[0:1], s[2:3]
	s_andn2_b64 vcc, exec, s[0:1]
	s_cbranch_vccnz .LBB0_1556
	s_waitcnt vmcnt(0)
	s_waitcnt vmcnt(0) lgkmcnt(0)
	s_barrier
	v_mov_b32_e32 v0, 0x20040
	ds_read_b32 v2, v0
	ds_read_b32 v3, v0 offset:16
	ds_read_b32 v5, v0 offset:8
	s_lshl_b32 s4, s33, 7
	s_add_u32 s4, s4, 0x3600
	v_lshl_add_u32 v0, v199, 2, s4
	v_mov_b32_e32 v6, 8
	v_mov_b32_e32 v7, 8
	s_waitcnt lgkmcnt(0)
	v_cmp_eq_u32_e32 vcc, 0, v3
	s_cbranch_vccnz .Lxl_orig_6
	v_cmp_lt_u32_e32 vcc, 32, v2
	s_cbranch_vccnz .Lxl_orig_6
	v_lshl_add_u32 v1, v5, 2, s4
	v_cmp_lt_u32_e32 vcc, v199, v2
	s_and_saveexec_b64 s[0:1], vcc
	s_cbranch_execz .LBB0_1555
	v_cmp_eq_u32_e32 vcc, 0, v199
	s_and_saveexec_b64 s[4:5], vcc
	global_store_dword v1, v6, s[92:93]
	s_mov_b64 exec, s[4:5]
	buffer_inv sc1
	s_mov_b32 s4, 0x20000
.Lxl_poll_6:
	global_load_dword v4, v0, s[92:93] sc1
	s_waitcnt vmcnt(0)
	v_cmp_gt_u32_e32 vcc, v7, v4
	s_cbranch_vccz .LBB0_1555
	s_sleep 1
	s_sub_u32 s4, s4, 1
	s_cmp_lg_u32 s4, 0
	s_cbranch_scc1 .Lxl_poll_6
	s_branch .LBB0_1555

.LBB0_1599:
	s_cmp_gt_i32 s69, 8
	s_cselect_b64 s[2:3], -1, 0
	s_and_b64 s[0:1], s[0:1], s[2:3]
	v_readlane_b32 s60, v255, 20
	s_andn2_b64 vcc, exec, s[0:1]
	v_readlane_b32 s61, v255, 21
	s_cbranch_vccnz .LBB0_1653
	s_waitcnt vmcnt(0)
	s_waitcnt vmcnt(0) lgkmcnt(0)
	s_barrier
	v_mov_b32_e32 v0, 0x20040
	ds_read_b32 v2, v0
	ds_read_b32 v3, v0 offset:16
	ds_read_b32 v5, v0 offset:8
	s_lshl_b32 s4, s33, 7
	s_add_u32 s4, s4, 0x3600
	v_lshl_add_u32 v0, v199, 2, s4
	v_mov_b32_e32 v6, 10
	v_mov_b32_e32 v7, 10
	s_waitcnt lgkmcnt(0)
	v_cmp_eq_u32_e32 vcc, 0, v3
	s_cbranch_vccnz .Lxl_orig_7
	v_cmp_lt_u32_e32 vcc, 32, v2
	s_cbranch_vccnz .Lxl_orig_7
	v_lshl_add_u32 v1, v5, 2, s4
	v_cmp_lt_u32_e32 vcc, v199, v2
	s_and_saveexec_b64 s[0:1], vcc
	s_cbranch_execz .LBB0_1652
	v_cmp_eq_u32_e32 vcc, 0, v199
	s_and_saveexec_b64 s[4:5], vcc
	global_store_dword v1, v6, s[92:93]
	s_mov_b64 exec, s[4:5]
	buffer_inv sc1
	s_mov_b32 s4, 0x20000

.LBB0_1674:
	s_cmp_lg_u32 s63, 4
	s_cbranch_scc1 .Lp8_noprog
	v_readfirstlane_b32 s1, v199
	s_nop 3
	s_cmp_lg_u32 s1, 0
	s_cbranch_scc1 .Lp8_noprog
	v_mov_b32_e32 v184, 0x20040
	ds_read_b32 v185, v184 offset:8
	ds_read_b32 v186, v184 offset:16
	s_lshl_b32 s1, s33, 7
	s_add_u32 s1, s1, 0x3600
	s_waitcnt lgkmcnt(0)
	v_cmp_ne_u32_e32 vcc, 0, v186
	s_cbranch_vccz .Lp8_noprog
	v_lshl_add_u32 v185, v185, 2, s1
	v_mov_b32_e32 v184, 11
	global_store_dword v185, v184, s[92:93]

.LBB0_1710:
	s_cmp_gt_i32 s69, 9
	s_cselect_b64 s[0:1], -1, 0
	s_and_b64 s[2:3], s[6:7], s[0:1]
	s_andn2_b64 vcc, exec, s[2:3]
	s_cbranch_vccnz .LBB0_1764
	s_waitcnt vmcnt(0)
	s_waitcnt vmcnt(0) lgkmcnt(0)
	s_barrier
	v_mov_b32_e32 v0, 0x20040
	ds_read_b32 v2, v0
	ds_read_b32 v3, v0 offset:16
	ds_read_b32 v5, v0 offset:8
	s_lshl_b32 s4, s33, 7
	s_add_u32 s4, s4, 0x3600
	v_lshl_add_u32 v0, v199, 2, s4
	v_mov_b32_e32 v6, 12
	v_mov_b32_e32 v7, 12
	s_waitcnt lgkmcnt(0)
	v_cmp_eq_u32_e32 vcc, 0, v3
	s_cbranch_vccnz .Lxl_orig_8
	v_cmp_lt_u32_e32 vcc, 32, v2
	s_cbranch_vccnz .Lxl_orig_8
	v_lshl_add_u32 v1, v5, 2, s4
	v_cmp_gt_u32_e32 vcc, 16, v5
	s_nop 1
	v_cndmask_b32_e64 v7, 11, 12, vcc
	v_cmp_lt_u32_e32 vcc, v199, v2
	s_and_saveexec_b64 s[2:3], vcc
	s_cbranch_execz .LBB0_1763
	v_cmp_eq_u32_e32 vcc, 0, v199
	s_and_saveexec_b64 s[4:5], vcc
	global_store_dword v1, v6, s[92:93]
	s_mov_b64 exec, s[4:5]
	buffer_inv sc1
	s_mov_b32 s4, 0x20000

.LBB0_1764:
	s_cmp_lt_i32 s68, 10
	s_cselect_b64 s[2:3], -1, 0
	s_and_b64 s[0:1], s[2:3], s[0:1]
	s_andn2_b64 vcc, exec, s[0:1]
	s_cbranch_vccnz .LBB0_1793
	s_xor_b32 s38, s38, 0x80
	s_cmpk_gt_i32 s38, 0xff
	v_readfirstlane_b32 s2, v199
	s_cbranch_scc1 .LBB0_1793
	s_ashr_i32 s20, s38, 31
	s_lshr_b32 s0, s20, 29
	s_add_i32 s5, s38, s0
	s_and_b32 s0, s5, -8
	s_sub_i32 s3, s38, s0
	s_cmp_gt_i32 s3, -1
	s_cbranch_scc0 .LBB0_1768
	s_lshl_b32 s4, s3, 5
	s_ashr_i32 s1, s5, 3
	s_cbranch_execz .LBB0_1769
	s_branch .LBB0_1770
